# cumulative: v64 plus second scalar pass (P1/P3/P9), divide-by-8 tile-index arithmetic, GLA step reorder and redundant pre-MFMA lgkmcnt waits removed
# speedup vs baseline: 1.0028x; 1.0028x over previous
; #define PG8_STAGE(bufoff, gbase, voff) do { _Pragma("unroll") for (int _i = 0; _i < 2; ++_i) \
;         __builtin_amdgcn_global_load_lds((const unsigned*)((const char*)(gbase) + (voff)[_i]), (PG8_LAS unsigned*)(lds + (bufoff) + ldsw + _i * 8192), 16, 0, 0); } while (0)
; #define PG8_LDA(dst, b, h) do { _Pragma("unroll") for (int m = 0; m < 4; ++m) _Pragma("unroll") for (int k = 0; k < 2; ++k) dst[m][k] = *(const PG8_LAS bf16x8*)(lds + PG8_SA(b, h) + aoff + m * 2048 + k * 1024); } while (0)
; #define PG8_LDB(dst, b, h) do { _Pragma("unroll") for (int n = 0; n < 2; ++n) _Pragma("unroll") for (int k = 0; k < 2; ++k) dst[n][k] = *(const PG8_LAS bf16x8*)(lds + PG8_SB(b, h) + boff + n * 2048 + k * 1024); } while (0)
; #define PG8_MMA(ai, bj, At, Bt) do { __builtin_amdgcn_s_setprio(1); _Pragma("unroll") for (int m = 0; m < 4; ++m) _Pragma("unroll") for (int n = 0; n < 2; ++n) _Pragma("unroll") for (int k = 0; k < 2; ++k) \
;         acc[ai][bj][m][n] = __builtin_amdgcn_mfma_f32_16x16x32_bf16(Bt[n][k], At[m][k], acc[ai][bj][m][n], 0, 0, 0); __builtin_amdgcn_s_setprio(0); } while (0)
; #define PG8_WAIT_V(n) asm volatile("s_waitcnt vmcnt(" #n ")" ::: "memory")
; template <class Epi, bool ALIGN_EPI, bool ABLK = false>
; __device__ __forceinline__ void gemm_phase(PG8_LAS unsigned char* lds, const Gemm g, const StaticOrder& S, const Epi& E) {
;     ...
;         const bool has_next = S.next(ui + 1, nxt);
;         const char* nA = has_next ? PG8_ABASE(nxt) : cA; const char* nB = has_next ? PG8_BBASE(nxt) : cB;
;         for (int t = 0; t < nt; t += 2) {
;             const bool last = (t == nt - 2);
;             const char* a1 = cA + (size_t)(t + 1) * kstepA;
;             const char* a2 = last ? nA : cA + (size_t)(t + 2) * kstepA; const char* b2 = last ? nB : cB + (size_t)(t + 2) * kstepB;
;             const char* a3 = a2 + kstepA; const char* b3 = b2 + kstepB;
;             PG8_LDB(B0, 0, 0); PG8_LDB(B1, 0, 1); PG8_SCHED; PG8_LDA(At, 0, 0); PG8_STAGE(PG8_SA(1, 1), a1 + hstepA, voffA);
;             PG8_WAIT_V(8); PG8_WAIT_L(0); PG8_BAR; PG8_MMA(0, 0, At, B0); PG8_MMA(0, 1, At, B1); PG8_BAR; PG8_SCHED;
;             PG8_LDA(At, 0, 1); PG8_STAGE(PG8_SB(0, 0), b2, voffB); PG8_STAGE(PG8_SB(0, 1), b2 + hstepB, voffB); PG8_STAGE(PG8_SA(0, 0), a2, voffA);
;             PG8_WAIT_V(8); PG8_WAIT_L(0); PG8_BAR; PG8_MMA(1, 0, At, B0); PG8_MMA(1, 1, At, B1); PG8_BAR; PG8_SCHED;
.LBB0_402:
	ds_read_b128 v[132:135], v251
	ds_read_b128 v[136:139], v251 offset:1024
	ds_read_b128 v[140:143], v251 offset:2048
	ds_read_b128 v[186:189], v251 offset:3072
	ds_read_b128 v[190:193], v251 offset:16384
	ds_read_b128 v[194:197], v251 offset:17408
	ds_read_b128 v[198:201], v251 offset:18432
	ds_read_b128 v[202:205], v251 offset:19456
	s_add_i32 m0, s55, 0xc000
	ds_read_b128 v[206:209], v183
	ds_read_b128 v[210:213], v183 offset:1024
	ds_read_b128 v[214:217], v183 offset:2048
	ds_read_b128 v[218:221], v183 offset:3072
	ds_read_b128 v[222:225], v183 offset:4096
	ds_read_b128 v[226:229], v183 offset:5120
	ds_read_b128 v[230:233], v183 offset:6144
	ds_read_b128 v[234:237], v183 offset:7168
	global_load_lds_dwordx4 v249, s[82:83]
	s_add_i32 m0, s55, 0xe000
	s_nop 0
	global_load_lds_dwordx4 v250, s[82:83]
	s_waitcnt vmcnt(8)
	s_waitcnt lgkmcnt(0)
	s_barrier
	s_setprio 1
	v_mfma_f32_16x16x32_bf16 v[126:129], v[132:135], v[206:209], v[126:129]
	v_mfma_f32_16x16x32_bf16 v[122:125], v[140:143], v[206:209], v[122:125]
	v_mfma_f32_16x16x32_bf16 v[118:121], v[132:135], v[214:217], v[118:121]
	v_mfma_f32_16x16x32_bf16 v[114:117], v[140:143], v[214:217], v[114:117]
	v_mfma_f32_16x16x32_bf16 v[110:113], v[132:135], v[222:225], v[110:113]
	v_mfma_f32_16x16x32_bf16 v[106:109], v[140:143], v[222:225], v[106:109]
	v_mfma_f32_16x16x32_bf16 v[102:105], v[132:135], v[230:233], v[102:105]
	v_mfma_f32_16x16x32_bf16 v[98:101], v[140:143], v[230:233], v[98:101]
	v_mfma_f32_16x16x32_bf16 v[126:129], v[136:139], v[210:213], v[126:129]
	v_mfma_f32_16x16x32_bf16 v[122:125], v[186:189], v[210:213], v[122:125]
	v_mfma_f32_16x16x32_bf16 v[118:121], v[136:139], v[218:221], v[118:121]
	v_mfma_f32_16x16x32_bf16 v[114:117], v[186:189], v[218:221], v[114:117]
	v_mfma_f32_16x16x32_bf16 v[110:113], v[136:139], v[226:229], v[110:113]
	v_mfma_f32_16x16x32_bf16 v[106:109], v[186:189], v[226:229], v[106:109]
	v_mfma_f32_16x16x32_bf16 v[102:105], v[136:139], v[234:237], v[102:105]
	v_mfma_f32_16x16x32_bf16 v[98:101], v[186:189], v[234:237], v[98:101]
	s_setprio 0
	s_setprio 1
	v_mfma_f32_16x16x32_bf16 v[94:97], v[190:193], v[206:209], v[94:97]
	s_add_i32 s71, s64, s9
	v_mfma_f32_16x16x32_bf16 v[90:93], v[198:201], v[206:209], v[90:93]
	s_mov_b32 m0, s71
	v_mfma_f32_16x16x32_bf16 v[86:89], v[190:193], v[214:217], v[86:89]
	s_add_u32 s48, s24, s46
	s_addc_u32 s49, s25, s47
	v_mfma_f32_16x16x32_bf16 v[82:85], v[198:201], v[214:217], v[82:85]
	s_cmp_eq_u32 s70, 12
	s_cselect_b32 s85, s41, s49
	v_mfma_f32_16x16x32_bf16 v[78:81], v[190:193], v[222:225], v[78:81]
	s_cselect_b32 s84, s66, s48
	s_cselect_b32 s49, s39, s69
	v_mfma_f32_16x16x32_bf16 v[74:77], v[198:201], v[222:225], v[74:77]
	s_cselect_b32 s48, s67, s68
	s_add_u32 s74, s48, 0x40000
	v_mfma_f32_16x16x32_bf16 v[70:73], v[190:193], v[230:233], v[70:73]
	s_addc_u32 s75, s49, 0
	v_mfma_f32_16x16x32_bf16 v[66:69], v[198:201], v[230:233], v[66:69]
	v_mfma_f32_16x16x32_bf16 v[94:97], v[194:197], v[210:213], v[94:97]
	v_mfma_f32_16x16x32_bf16 v[90:93], v[202:205], v[210:213], v[90:93]
	v_mfma_f32_16x16x32_bf16 v[86:89], v[194:197], v[218:221], v[86:89]
	v_mfma_f32_16x16x32_bf16 v[82:85], v[202:205], v[218:221], v[82:85]
	v_mfma_f32_16x16x32_bf16 v[78:81], v[194:197], v[226:229], v[78:81]
	v_mfma_f32_16x16x32_bf16 v[74:77], v[202:205], v[226:229], v[74:77]
	v_mfma_f32_16x16x32_bf16 v[70:73], v[194:197], v[234:237], v[70:73]
	v_mfma_f32_16x16x32_bf16 v[66:69], v[202:205], v[234:237], v[66:69]
	s_setprio 0
	s_barrier
	ds_read_b128 v[206:209], v183 offset:16384
	ds_read_b128 v[210:213], v183 offset:17408
	ds_read_b128 v[214:217], v183 offset:18432
	ds_read_b128 v[218:221], v183 offset:19456
	ds_read_b128 v[222:225], v183 offset:20480
	ds_read_b128 v[226:229], v183 offset:21504
	ds_read_b128 v[230:233], v183 offset:22528
	ds_read_b128 v[234:237], v183 offset:23552
	global_load_lds_dwordx4 v148, s[48:49]
	s_add_i32 m0, s71, 0x2000
	s_add_i32 s71, s65, s9
	global_load_lds_dwordx4 v150, s[48:49]
	s_mov_b32 m0, s71
	s_nop 0
	global_load_lds_dwordx4 v148, s[74:75]
	s_add_i32 m0, s71, 0x2000
	s_nop 0
	global_load_lds_dwordx4 v150, s[74:75]
	s_mov_b32 m0, s55
	s_mov_b64 s[72:73], 0x2000
	global_load_lds_dwordx4 v146, s[84:85]
	s_mov_b32 m0, s56
	s_nop 0
	global_load_lds_dwordx4 v244, s[84:85]
	s_waitcnt vmcnt(8)
	s_waitcnt lgkmcnt(0)
	s_barrier
	s_setprio 1
	v_mfma_f32_16x16x32_bf16 v[62:65], v[132:135], v[206:209], v[62:65]
	v_mfma_f32_16x16x32_bf16 v[58:61], v[140:143], v[206:209], v[58:61]
	v_mfma_f32_16x16x32_bf16 v[54:57], v[132:135], v[214:217], v[54:57]
	v_mfma_f32_16x16x32_bf16 v[50:53], v[140:143], v[214:217], v[50:53]
	v_mfma_f32_16x16x32_bf16 v[46:49], v[132:135], v[222:225], v[46:49]
	v_mfma_f32_16x16x32_bf16 v[42:45], v[140:143], v[222:225], v[42:45]
	v_mfma_f32_16x16x32_bf16 v[38:41], v[132:135], v[230:233], v[38:41]
	v_mfma_f32_16x16x32_bf16 v[34:37], v[140:143], v[230:233], v[34:37]
	v_mfma_f32_16x16x32_bf16 v[62:65], v[136:139], v[210:213], v[62:65]
	v_mfma_f32_16x16x32_bf16 v[58:61], v[186:189], v[210:213], v[58:61]
	v_mfma_f32_16x16x32_bf16 v[54:57], v[136:139], v[218:221], v[54:57]
	v_mfma_f32_16x16x32_bf16 v[50:53], v[186:189], v[218:221], v[50:53]
	v_mfma_f32_16x16x32_bf16 v[46:49], v[136:139], v[226:229], v[46:49]
	v_mfma_f32_16x16x32_bf16 v[42:45], v[186:189], v[226:229], v[42:45]
	v_mfma_f32_16x16x32_bf16 v[38:41], v[136:139], v[234:237], v[38:41]
	v_mfma_f32_16x16x32_bf16 v[34:37], v[186:189], v[234:237], v[34:37]
	s_setprio 0
	s_setprio 1
	v_mfma_f32_16x16x32_bf16 v[30:33], v[190:193], v[206:209], v[30:33]
	s_add_i32 s71, 0, 0x18000
	v_mfma_f32_16x16x32_bf16 v[26:29], v[198:201], v[206:209], v[26:29]
	s_add_i32 s74, 0, 0x1c000
	v_mfma_f32_16x16x32_bf16 v[22:25], v[190:193], v[214:217], v[22:25]
	v_mfma_f32_16x16x32_bf16 v[18:21], v[198:201], v[214:217], v[18:21]
	v_mfma_f32_16x16x32_bf16 v[14:17], v[190:193], v[222:225], v[14:17]
	v_mfma_f32_16x16x32_bf16 v[10:13], v[198:201], v[222:225], v[10:13]
	v_mfma_f32_16x16x32_bf16 v[6:9], v[190:193], v[230:233], v[6:9]
	v_mfma_f32_16x16x32_bf16 v[2:5], v[198:201], v[230:233], v[2:5]
	v_mfma_f32_16x16x32_bf16 v[30:33], v[194:197], v[210:213], v[30:33]
	v_mfma_f32_16x16x32_bf16 v[26:29], v[202:205], v[210:213], v[26:29]
	v_mfma_f32_16x16x32_bf16 v[22:25], v[194:197], v[218:221], v[22:25]
	v_mfma_f32_16x16x32_bf16 v[18:21], v[202:205], v[218:221], v[18:21]
	v_mfma_f32_16x16x32_bf16 v[14:17], v[194:197], v[226:229], v[14:17]
	v_mfma_f32_16x16x32_bf16 v[10:13], v[202:205], v[226:229], v[10:13]
	v_mfma_f32_16x16x32_bf16 v[6:9], v[194:197], v[234:237], v[6:9]
	v_mfma_f32_16x16x32_bf16 v[2:5], v[202:205], v[234:237], v[2:5]
	s_setprio 0
	s_barrier
; #define PG8_STAGE(bufoff, gbase, voff) do { _Pragma("unroll") for (int _i = 0; _i < 2; ++_i) \
;         __builtin_amdgcn_global_load_lds((const unsigned*)((const char*)(gbase) + (voff)[_i]), (PG8_LAS unsigned*)(lds + (bufoff) + ldsw + _i * 8192), 16, 0, 0); } while (0)
; #define PG8_LDA(dst, b, h) do { _Pragma("unroll") for (int m = 0; m < 4; ++m) _Pragma("unroll") for (int k = 0; k < 2; ++k) dst[m][k] = *(const PG8_LAS bf16x8*)(lds + PG8_SA(b, h) + aoff + m * 2048 + k * 1024); } while (0)
; #define PG8_LDB(dst, b, h) do { _Pragma("unroll") for (int n = 0; n < 2; ++n) _Pragma("unroll") for (int k = 0; k < 2; ++k) dst[n][k] = *(const PG8_LAS bf16x8*)(lds + PG8_SB(b, h) + boff + n * 2048 + k * 1024); } while (0)
; #define PG8_MMA(ai, bj, At, Bt) do { __builtin_amdgcn_s_setprio(1); _Pragma("unroll") for (int m = 0; m < 4; ++m) _Pragma("unroll") for (int n = 0; n < 2; ++n) _Pragma("unroll") for (int k = 0; k < 2; ++k) \
;         acc[ai][bj][m][n] = __builtin_amdgcn_mfma_f32_16x16x32_bf16(Bt[n][k], At[m][k], acc[ai][bj][m][n], 0, 0, 0); __builtin_amdgcn_s_setprio(0); } while (0)
; #define PG8_WAIT_V(n) asm volatile("s_waitcnt vmcnt(" #n ")" ::: "memory")
; #define PG8_WAIT_L(n) asm volatile("s_waitcnt lgkmcnt(" #n ")" ::: "memory")
; #define PG8_BAR __builtin_amdgcn_s_barrier()
; #define PG8_SCHED __builtin_amdgcn_sched_barrier(0)
; template <class Epi, bool ALIGN_EPI, bool ABLK = false>
; __device__ __forceinline__ void gemm_phase(PG8_LAS unsigned char* lds, const Gemm g, const StaticOrder& S, const Epi& E) {
;     ...
;             PG8_LDB(B0, 1, 0); PG8_LDB(B1, 1, 1); PG8_SCHED; PG8_LDA(At, 1, 0); PG8_STAGE(PG8_SA(0, 1), a2 + hstepA, voffA);
;             PG8_WAIT_V(8); PG8_WAIT_L(0); PG8_BAR; PG8_MMA(0, 0, At, B0); PG8_MMA(0, 1, At, B1); PG8_BAR; PG8_SCHED;
;             PG8_LDA(At, 1, 1); PG8_STAGE(PG8_SB(1, 0), b3, voffB); PG8_STAGE(PG8_SB(1, 1), b3 + hstepB, voffB); PG8_STAGE(PG8_SA(1, 0), a3, voffA);
;             PG8_WAIT_V(8); PG8_WAIT_L(0); PG8_BAR; PG8_MMA(1, 0, At, B0); PG8_MMA(1, 1, At, B1); PG8_BAR; PG8_SCHED;
	ds_read_b128 v[132:135], v251 offset:32768
	ds_read_b128 v[136:139], v251 offset:33792
	ds_read_b128 v[140:143], v251 offset:34816
	ds_read_b128 v[186:189], v251 offset:35840
	ds_read_b128 v[190:193], v251 offset:49152
	ds_read_b128 v[194:197], v251 offset:50176
	ds_read_b128 v[198:201], v251 offset:51200
	ds_read_b128 v[202:205], v251 offset:52224
	s_mov_b32 m0, s57
	ds_read_b128 v[206:209], v183 offset:32768
	ds_read_b128 v[210:213], v183 offset:33792
	ds_read_b128 v[214:217], v183 offset:34816
	ds_read_b128 v[218:221], v183 offset:35840
	ds_read_b128 v[222:225], v183 offset:36864
	ds_read_b128 v[226:229], v183 offset:37888
	ds_read_b128 v[230:233], v183 offset:38912
	ds_read_b128 v[234:237], v183 offset:39936
	global_load_lds_dwordx4 v245, s[84:85]
	s_mov_b32 m0, s58
	s_nop 0
	global_load_lds_dwordx4 v246, s[84:85]
	s_waitcnt vmcnt(8)
	s_waitcnt lgkmcnt(0)
	s_barrier
	s_setprio 1
	v_mfma_f32_16x16x32_bf16 v[126:129], v[132:135], v[206:209], v[126:129]
	v_mfma_f32_16x16x32_bf16 v[122:125], v[140:143], v[206:209], v[122:125]
	v_mfma_f32_16x16x32_bf16 v[118:121], v[132:135], v[214:217], v[118:121]
	v_mfma_f32_16x16x32_bf16 v[114:117], v[140:143], v[214:217], v[114:117]
	v_mfma_f32_16x16x32_bf16 v[110:113], v[132:135], v[222:225], v[110:113]
	v_mfma_f32_16x16x32_bf16 v[106:109], v[140:143], v[222:225], v[106:109]
	v_mfma_f32_16x16x32_bf16 v[102:105], v[132:135], v[230:233], v[102:105]
	v_mfma_f32_16x16x32_bf16 v[98:101], v[140:143], v[230:233], v[98:101]
	v_mfma_f32_16x16x32_bf16 v[126:129], v[136:139], v[210:213], v[126:129]
	v_mfma_f32_16x16x32_bf16 v[122:125], v[186:189], v[210:213], v[122:125]
	v_mfma_f32_16x16x32_bf16 v[118:121], v[136:139], v[218:221], v[118:121]
	v_mfma_f32_16x16x32_bf16 v[114:117], v[186:189], v[218:221], v[114:117]
	v_mfma_f32_16x16x32_bf16 v[110:113], v[136:139], v[226:229], v[110:113]
	v_mfma_f32_16x16x32_bf16 v[106:109], v[186:189], v[226:229], v[106:109]
	v_mfma_f32_16x16x32_bf16 v[102:105], v[136:139], v[234:237], v[102:105]
	v_mfma_f32_16x16x32_bf16 v[98:101], v[186:189], v[234:237], v[98:101]
	s_setprio 0
	s_setprio 1
	v_mfma_f32_16x16x32_bf16 v[94:97], v[190:193], v[206:209], v[94:97]
	s_add_i32 s71, s71, s9
	v_mfma_f32_16x16x32_bf16 v[90:93], v[198:201], v[206:209], v[90:93]
	s_add_u32 s86, s48, s28
	v_mfma_f32_16x16x32_bf16 v[86:89], v[190:193], v[214:217], v[86:89]
	s_addc_u32 s87, s49, s29
	v_mfma_f32_16x16x32_bf16 v[82:85], v[198:201], v[214:217], v[82:85]
	s_mov_b32 m0, s71
	v_mfma_f32_16x16x32_bf16 v[78:81], v[190:193], v[222:225], v[78:81]
	s_add_u32 s48, s48, 0x40080
	s_addc_u32 s49, s49, 0
	v_mfma_f32_16x16x32_bf16 v[74:77], v[198:201], v[222:225], v[74:77]
	v_mfma_f32_16x16x32_bf16 v[70:73], v[190:193], v[230:233], v[70:73]
	v_mfma_f32_16x16x32_bf16 v[66:69], v[198:201], v[230:233], v[66:69]
	v_mfma_f32_16x16x32_bf16 v[94:97], v[194:197], v[210:213], v[94:97]
	v_mfma_f32_16x16x32_bf16 v[90:93], v[202:205], v[210:213], v[90:93]
	v_mfma_f32_16x16x32_bf16 v[86:89], v[194:197], v[218:221], v[86:89]
	v_mfma_f32_16x16x32_bf16 v[82:85], v[202:205], v[218:221], v[82:85]
	v_mfma_f32_16x16x32_bf16 v[78:81], v[194:197], v[226:229], v[78:81]
	v_mfma_f32_16x16x32_bf16 v[74:77], v[202:205], v[226:229], v[74:77]
	v_mfma_f32_16x16x32_bf16 v[70:73], v[194:197], v[234:237], v[70:73]
	v_mfma_f32_16x16x32_bf16 v[66:69], v[202:205], v[234:237], v[66:69]
	s_setprio 0
	s_barrier
	ds_read_b128 v[206:209], v183 offset:49152
	ds_read_b128 v[210:213], v183 offset:50176
	ds_read_b128 v[214:217], v183 offset:51200
	ds_read_b128 v[218:221], v183 offset:52224
	ds_read_b128 v[222:225], v183 offset:53248
	ds_read_b128 v[226:229], v183 offset:54272
	ds_read_b128 v[230:233], v183 offset:55296
	ds_read_b128 v[234:237], v183 offset:56320
	global_load_lds_dwordx4 v148, s[86:87]
	s_add_i32 m0, s71, 0x2000
	s_add_i32 s71, s74, s9
	global_load_lds_dwordx4 v150, s[86:87]
	s_mov_b32 m0, s71
	s_nop 0
	global_load_lds_dwordx4 v148, s[48:49]
	s_add_i32 m0, s71, 0x2000
	s_nop 0
	global_load_lds_dwordx4 v150, s[48:49]
	s_mov_b32 m0, s59
	s_nop 0
	global_load_lds_dwordx4 v247, s[84:85]
	s_mov_b32 m0, s61
	s_nop 0
	global_load_lds_dwordx4 v248, s[84:85]
	s_waitcnt vmcnt(8)
	s_waitcnt lgkmcnt(0)
	s_barrier
	s_setprio 1
	v_mfma_f32_16x16x32_bf16 v[62:65], v[132:135], v[206:209], v[62:65]
	v_mfma_f32_16x16x32_bf16 v[58:61], v[140:143], v[206:209], v[58:61]
	v_mfma_f32_16x16x32_bf16 v[54:57], v[132:135], v[214:217], v[54:57]
	v_mfma_f32_16x16x32_bf16 v[50:53], v[140:143], v[214:217], v[50:53]
	v_mfma_f32_16x16x32_bf16 v[46:49], v[132:135], v[222:225], v[46:49]
	v_mfma_f32_16x16x32_bf16 v[42:45], v[140:143], v[222:225], v[42:45]
	v_mfma_f32_16x16x32_bf16 v[38:41], v[132:135], v[230:233], v[38:41]
	v_mfma_f32_16x16x32_bf16 v[34:37], v[140:143], v[230:233], v[34:37]
	v_mfma_f32_16x16x32_bf16 v[62:65], v[136:139], v[210:213], v[62:65]
	v_mfma_f32_16x16x32_bf16 v[58:61], v[186:189], v[210:213], v[58:61]
	v_mfma_f32_16x16x32_bf16 v[54:57], v[136:139], v[218:221], v[54:57]
	v_mfma_f32_16x16x32_bf16 v[50:53], v[186:189], v[218:221], v[50:53]
	v_mfma_f32_16x16x32_bf16 v[46:49], v[136:139], v[226:229], v[46:49]
	v_mfma_f32_16x16x32_bf16 v[42:45], v[186:189], v[226:229], v[42:45]
	v_mfma_f32_16x16x32_bf16 v[38:41], v[136:139], v[234:237], v[38:41]
	v_mfma_f32_16x16x32_bf16 v[34:37], v[186:189], v[234:237], v[34:37]
	s_setprio 0
	s_setprio 1
	v_mfma_f32_16x16x32_bf16 v[30:33], v[190:193], v[206:209], v[30:33]
	s_add_i32 s70, s70, 2
	v_mfma_f32_16x16x32_bf16 v[26:29], v[198:201], v[206:209], v[26:29]
	s_add_u32 s68, s68, 0x100
	v_mfma_f32_16x16x32_bf16 v[22:25], v[190:193], v[214:217], v[22:25]
	s_addc_u32 s69, s69, 0
	v_mfma_f32_16x16x32_bf16 v[18:21], v[198:201], v[214:217], v[18:21]
	s_add_u32 s46, s46, 0x10000
	v_mfma_f32_16x16x32_bf16 v[14:17], v[190:193], v[222:225], v[14:17]
	s_addc_u32 s47, s47, 0
	v_mfma_f32_16x16x32_bf16 v[10:13], v[198:201], v[222:225], v[10:13]
	s_add_u32 s82, s82, 0x10000
	v_mfma_f32_16x16x32_bf16 v[6:9], v[190:193], v[230:233], v[6:9]
	s_addc_u32 s83, s83, 0
	v_mfma_f32_16x16x32_bf16 v[2:5], v[198:201], v[230:233], v[2:5]
	s_mov_b64 s[48:49], 0x10000
	v_mfma_f32_16x16x32_bf16 v[30:33], v[194:197], v[210:213], v[30:33]
	s_cmp_gt_u32 s70, 13
	v_mfma_f32_16x16x32_bf16 v[26:29], v[202:205], v[210:213], v[26:29]
	v_mfma_f32_16x16x32_bf16 v[22:25], v[194:197], v[218:221], v[22:25]
	v_mfma_f32_16x16x32_bf16 v[18:21], v[202:205], v[218:221], v[18:21]
	v_mfma_f32_16x16x32_bf16 v[14:17], v[194:197], v[226:229], v[14:17]
	v_mfma_f32_16x16x32_bf16 v[10:13], v[202:205], v[226:229], v[10:13]
	v_mfma_f32_16x16x32_bf16 v[6:9], v[194:197], v[234:237], v[6:9]
	v_mfma_f32_16x16x32_bf16 v[2:5], v[202:205], v[234:237], v[2:5]
	s_setprio 0
	s_barrier
	s_cbranch_scc0 .LBB0_402
	s_and_b64 vcc, exec, s[36:37]
	s_cbranch_vccz .LBB0_405
	s_barrier

; #define PG8_STAGE(bufoff, gbase, voff) do { _Pragma("unroll") for (int _i = 0; _i < 2; ++_i) \
;         __builtin_amdgcn_global_load_lds((const unsigned*)((const char*)(gbase) + (voff)[_i]), (PG8_LAS unsigned*)(lds + (bufoff) + ldsw + _i * 8192), 16, 0, 0); } while (0)
; #define PG8_LDA(dst, b, h) do { _Pragma("unroll") for (int m = 0; m < 4; ++m) _Pragma("unroll") for (int k = 0; k < 2; ++k) dst[m][k] = *(const PG8_LAS bf16x8*)(lds + PG8_SA(b, h) + aoff + m * 2048 + k * 1024); } while (0)
; #define PG8_LDB(dst, b, h) do { _Pragma("unroll") for (int n = 0; n < 2; ++n) _Pragma("unroll") for (int k = 0; k < 2; ++k) dst[n][k] = *(const PG8_LAS bf16x8*)(lds + PG8_SB(b, h) + boff + n * 2048 + k * 1024); } while (0)
; #define PG8_MMA(ai, bj, At, Bt) do { __builtin_amdgcn_s_setprio(1); _Pragma("unroll") for (int m = 0; m < 4; ++m) _Pragma("unroll") for (int n = 0; n < 2; ++n) _Pragma("unroll") for (int k = 0; k < 2; ++k) \
;         acc[ai][bj][m][n] = __builtin_amdgcn_mfma_f32_16x16x32_bf16(Bt[n][k], At[m][k], acc[ai][bj][m][n], 0, 0, 0); __builtin_amdgcn_s_setprio(0); } while (0)
; #define PG8_WAIT_V(n) asm volatile("s_waitcnt vmcnt(" #n ")" ::: "memory")
; template <class Epi, bool ALIGN_EPI, bool ABLK = false>
; __device__ __forceinline__ void gemm_phase(PG8_LAS unsigned char* lds, const Gemm g, const StaticOrder& S, const Epi& E) {
;     ...
;         const bool has_next = S.next(ui + 1, nxt);
;         const char* nA = has_next ? PG8_ABASE(nxt) : cA; const char* nB = has_next ? PG8_BBASE(nxt) : cB;
;         for (int t = 0; t < nt; t += 2) {
;             const bool last = (t == nt - 2);
;             const char* a1 = cA + (size_t)(t + 1) * kstepA;
;             const char* a2 = last ? nA : cA + (size_t)(t + 2) * kstepA; const char* b2 = last ? nB : cB + (size_t)(t + 2) * kstepB;
;             const char* a3 = a2 + kstepA; const char* b3 = b2 + kstepB;
;             PG8_LDB(B0, 0, 0); PG8_LDB(B1, 0, 1); PG8_SCHED; PG8_LDA(At, 0, 0); PG8_STAGE(PG8_SA(1, 1), a1 + hstepA, voffA);
;             PG8_WAIT_V(8); PG8_WAIT_L(0); PG8_BAR; PG8_MMA(0, 0, At, B0); PG8_MMA(0, 1, At, B1); PG8_BAR; PG8_SCHED;
;             PG8_LDA(At, 0, 1); PG8_STAGE(PG8_SB(0, 0), b2, voffB); PG8_STAGE(PG8_SB(0, 1), b2 + hstepB, voffB); PG8_STAGE(PG8_SA(0, 0), a2, voffA);
;             PG8_WAIT_V(8); PG8_WAIT_L(0); PG8_BAR; PG8_MMA(1, 0, At, B0); PG8_MMA(1, 1, At, B1); PG8_BAR; PG8_SCHED;
.LBB0_818:
	ds_read_b128 v[132:135], v153
	ds_read_b128 v[136:139], v153 offset:1024
	ds_read_b128 v[140:143], v153 offset:2048
	ds_read_b128 v[144:147], v153 offset:3072
	ds_read_b128 v[148:151], v153 offset:16384
	ds_read_b128 v[178:181], v153 offset:17408
	ds_read_b128 v[182:185], v153 offset:18432
	ds_read_b128 v[212:215], v153 offset:19456
	s_add_u32 s12, s38, s10
	s_addc_u32 s13, s39, s11
	s_sub_u32 s98, s12, 0x10000
	s_subb_u32 s99, s13, 0
	s_add_i32 m0, s35, 0xc000
	ds_read_b128 v[216:219], v205
	ds_read_b128 v[220:223], v205 offset:1024
	ds_read_b128 v[224:227], v205 offset:2048
	ds_read_b128 v[228:231], v205 offset:3072
	ds_read_b128 v[232:235], v205 offset:4096
	ds_read_b128 v[236:239], v205 offset:5120
	ds_read_b128 v[240:243], v205 offset:6144
	ds_read_b128 v[244:247], v205 offset:7168
	global_load_lds_dwordx4 v253, s[98:99]
	s_add_i32 m0, s35, 0xe000
	s_nop 0
	global_load_lds_dwordx4 v152, s[98:99]
	s_waitcnt vmcnt(8)
	s_waitcnt lgkmcnt(0)
	s_barrier
	s_setprio 1
	v_mfma_f32_16x16x32_bf16 v[126:129], v[132:135], v[216:219], v[126:129]
	v_mfma_f32_16x16x32_bf16 v[122:125], v[140:143], v[216:219], v[122:125]
	v_mfma_f32_16x16x32_bf16 v[118:121], v[132:135], v[224:227], v[118:121]
	v_mfma_f32_16x16x32_bf16 v[114:117], v[140:143], v[224:227], v[114:117]
	v_mfma_f32_16x16x32_bf16 v[110:113], v[132:135], v[232:235], v[110:113]
	v_mfma_f32_16x16x32_bf16 v[106:109], v[140:143], v[232:235], v[106:109]
	v_mfma_f32_16x16x32_bf16 v[102:105], v[132:135], v[240:243], v[102:105]
	v_mfma_f32_16x16x32_bf16 v[98:101], v[140:143], v[240:243], v[98:101]
	v_mfma_f32_16x16x32_bf16 v[126:129], v[136:139], v[220:223], v[126:129]
	v_mfma_f32_16x16x32_bf16 v[122:125], v[144:147], v[220:223], v[122:125]
	v_mfma_f32_16x16x32_bf16 v[118:121], v[136:139], v[228:231], v[118:121]
	v_mfma_f32_16x16x32_bf16 v[114:117], v[144:147], v[228:231], v[114:117]
	v_mfma_f32_16x16x32_bf16 v[110:113], v[136:139], v[236:239], v[110:113]
	v_mfma_f32_16x16x32_bf16 v[106:109], v[144:147], v[236:239], v[106:109]
	v_mfma_f32_16x16x32_bf16 v[102:105], v[136:139], v[244:247], v[102:105]
	v_mfma_f32_16x16x32_bf16 v[98:101], v[144:147], v[244:247], v[98:101]
	s_setprio 0
	s_setprio 1
	v_mfma_f32_16x16x32_bf16 v[94:97], v[148:151], v[216:219], v[94:97]
	s_add_i32 s68, s42, s31
	v_mfma_f32_16x16x32_bf16 v[90:93], v[182:185], v[216:219], v[90:93]
	s_mov_b32 m0, s68
	v_mfma_f32_16x16x32_bf16 v[86:89], v[148:151], v[224:227], v[86:89]
	s_cmp_eq_u32 s65, 12
	s_cselect_b32 s101, s33, s13
	v_mfma_f32_16x16x32_bf16 v[82:85], v[182:185], v[224:227], v[82:85]
	s_cselect_b32 s100, s57, s12
	s_cselect_b32 s13, s55, s64
	v_mfma_f32_16x16x32_bf16 v[78:81], v[148:151], v[232:235], v[78:81]
	s_cselect_b32 s12, s62, s63
	v_mfma_f32_16x16x32_bf16 v[74:77], v[182:185], v[232:235], v[74:77]
	v_mfma_f32_16x16x32_bf16 v[70:73], v[148:151], v[240:243], v[70:73]
	v_mfma_f32_16x16x32_bf16 v[66:69], v[182:185], v[240:243], v[66:69]
	v_mfma_f32_16x16x32_bf16 v[94:97], v[178:181], v[220:223], v[94:97]
	v_mfma_f32_16x16x32_bf16 v[90:93], v[212:215], v[220:223], v[90:93]
	v_mfma_f32_16x16x32_bf16 v[86:89], v[178:181], v[228:231], v[86:89]
	v_mfma_f32_16x16x32_bf16 v[82:85], v[212:215], v[228:231], v[82:85]
	v_mfma_f32_16x16x32_bf16 v[78:81], v[178:181], v[236:239], v[78:81]
	v_mfma_f32_16x16x32_bf16 v[74:77], v[212:215], v[236:239], v[74:77]
	v_mfma_f32_16x16x32_bf16 v[70:73], v[178:181], v[244:247], v[70:73]
	v_mfma_f32_16x16x32_bf16 v[66:69], v[212:215], v[244:247], v[66:69]
	s_setprio 0
	s_barrier
	ds_read_b128 v[216:219], v205 offset:16384
	ds_read_b128 v[220:223], v205 offset:17408
	ds_read_b128 v[224:227], v205 offset:18432
	ds_read_b128 v[228:231], v205 offset:19456
	ds_read_b128 v[232:235], v205 offset:20480
	ds_read_b128 v[236:239], v205 offset:21504
	ds_read_b128 v[240:243], v205 offset:22528
	ds_read_b128 v[244:247], v205 offset:23552
	global_load_lds_dwordx4 v156, s[12:13]
	s_add_i32 m0, s68, 0x2000
	s_add_u32 s68, s12, 0x40000
	s_addc_u32 s69, s13, 0
	s_add_i32 s70, s43, s31
	global_load_lds_dwordx4 v158, s[12:13]
	s_mov_b32 m0, s70
	s_nop 0
	global_load_lds_dwordx4 v156, s[68:69]
	s_add_i32 m0, s70, 0x2000
	s_nop 0
	global_load_lds_dwordx4 v158, s[68:69]
	s_mov_b32 m0, s35
	s_mov_b64 s[66:67], 0x2000
	global_load_lds_dwordx4 v154, s[100:101]
	s_mov_b32 m0, s18
	s_nop 0
	global_load_lds_dwordx4 v248, s[100:101]
	s_waitcnt vmcnt(8)
	s_waitcnt lgkmcnt(0)
	s_barrier
	s_setprio 1
	v_mfma_f32_16x16x32_bf16 v[62:65], v[132:135], v[216:219], v[62:65]
	v_mfma_f32_16x16x32_bf16 v[58:61], v[140:143], v[216:219], v[58:61]
	v_mfma_f32_16x16x32_bf16 v[54:57], v[132:135], v[224:227], v[54:57]
	v_mfma_f32_16x16x32_bf16 v[50:53], v[140:143], v[224:227], v[50:53]
	v_mfma_f32_16x16x32_bf16 v[46:49], v[132:135], v[232:235], v[46:49]
	v_mfma_f32_16x16x32_bf16 v[42:45], v[140:143], v[232:235], v[42:45]
	v_mfma_f32_16x16x32_bf16 v[38:41], v[132:135], v[240:243], v[38:41]
	v_mfma_f32_16x16x32_bf16 v[34:37], v[140:143], v[240:243], v[34:37]
	v_mfma_f32_16x16x32_bf16 v[62:65], v[136:139], v[220:223], v[62:65]
	v_mfma_f32_16x16x32_bf16 v[58:61], v[144:147], v[220:223], v[58:61]
	v_mfma_f32_16x16x32_bf16 v[54:57], v[136:139], v[228:231], v[54:57]
	v_mfma_f32_16x16x32_bf16 v[50:53], v[144:147], v[228:231], v[50:53]
	v_mfma_f32_16x16x32_bf16 v[46:49], v[136:139], v[236:239], v[46:49]
	v_mfma_f32_16x16x32_bf16 v[42:45], v[144:147], v[236:239], v[42:45]
	v_mfma_f32_16x16x32_bf16 v[38:41], v[136:139], v[244:247], v[38:41]
	v_mfma_f32_16x16x32_bf16 v[34:37], v[144:147], v[244:247], v[34:37]
	s_setprio 0
	s_setprio 1
	v_mfma_f32_16x16x32_bf16 v[30:33], v[148:151], v[216:219], v[30:33]
	s_add_i32 s68, 0, 0x18000
	v_mfma_f32_16x16x32_bf16 v[26:29], v[182:185], v[216:219], v[26:29]
	s_add_i32 s69, 0, 0x1c000
	v_mfma_f32_16x16x32_bf16 v[22:25], v[148:151], v[224:227], v[22:25]
	v_mfma_f32_16x16x32_bf16 v[18:21], v[182:185], v[224:227], v[18:21]
	v_mfma_f32_16x16x32_bf16 v[14:17], v[148:151], v[232:235], v[14:17]
	v_mfma_f32_16x16x32_bf16 v[10:13], v[182:185], v[232:235], v[10:13]
	v_mfma_f32_16x16x32_bf16 v[6:9], v[148:151], v[240:243], v[6:9]
	v_mfma_f32_16x16x32_bf16 v[2:5], v[182:185], v[240:243], v[2:5]
	v_mfma_f32_16x16x32_bf16 v[30:33], v[178:181], v[220:223], v[30:33]
	v_mfma_f32_16x16x32_bf16 v[26:29], v[212:215], v[220:223], v[26:29]
	v_mfma_f32_16x16x32_bf16 v[22:25], v[178:181], v[228:231], v[22:25]
	v_mfma_f32_16x16x32_bf16 v[18:21], v[212:215], v[228:231], v[18:21]
	v_mfma_f32_16x16x32_bf16 v[14:17], v[178:181], v[236:239], v[14:17]
	v_mfma_f32_16x16x32_bf16 v[10:13], v[212:215], v[236:239], v[10:13]
	v_mfma_f32_16x16x32_bf16 v[6:9], v[178:181], v[244:247], v[6:9]
	v_mfma_f32_16x16x32_bf16 v[2:5], v[212:215], v[244:247], v[2:5]
	s_setprio 0
	s_barrier
; #define PG8_STAGE(bufoff, gbase, voff) do { _Pragma("unroll") for (int _i = 0; _i < 2; ++_i) \
;         __builtin_amdgcn_global_load_lds((const unsigned*)((const char*)(gbase) + (voff)[_i]), (PG8_LAS unsigned*)(lds + (bufoff) + ldsw + _i * 8192), 16, 0, 0); } while (0)
; #define PG8_LDA(dst, b, h) do { _Pragma("unroll") for (int m = 0; m < 4; ++m) _Pragma("unroll") for (int k = 0; k < 2; ++k) dst[m][k] = *(const PG8_LAS bf16x8*)(lds + PG8_SA(b, h) + aoff + m * 2048 + k * 1024); } while (0)
; #define PG8_LDB(dst, b, h) do { _Pragma("unroll") for (int n = 0; n < 2; ++n) _Pragma("unroll") for (int k = 0; k < 2; ++k) dst[n][k] = *(const PG8_LAS bf16x8*)(lds + PG8_SB(b, h) + boff + n * 2048 + k * 1024); } while (0)
; #define PG8_MMA(ai, bj, At, Bt) do { __builtin_amdgcn_s_setprio(1); _Pragma("unroll") for (int m = 0; m < 4; ++m) _Pragma("unroll") for (int n = 0; n < 2; ++n) _Pragma("unroll") for (int k = 0; k < 2; ++k) \
;         acc[ai][bj][m][n] = __builtin_amdgcn_mfma_f32_16x16x32_bf16(Bt[n][k], At[m][k], acc[ai][bj][m][n], 0, 0, 0); __builtin_amdgcn_s_setprio(0); } while (0)
; #define PG8_WAIT_V(n) asm volatile("s_waitcnt vmcnt(" #n ")" ::: "memory")
; #define PG8_WAIT_L(n) asm volatile("s_waitcnt lgkmcnt(" #n ")" ::: "memory")
; #define PG8_BAR __builtin_amdgcn_s_barrier()
; #define PG8_SCHED __builtin_amdgcn_sched_barrier(0)
; template <class Epi, bool ALIGN_EPI, bool ABLK = false>
; __device__ __forceinline__ void gemm_phase(PG8_LAS unsigned char* lds, const Gemm g, const StaticOrder& S, const Epi& E) {
;     ...
;             PG8_LDB(B0, 1, 0); PG8_LDB(B1, 1, 1); PG8_SCHED; PG8_LDA(At, 1, 0); PG8_STAGE(PG8_SA(0, 1), a2 + hstepA, voffA);
;             PG8_WAIT_V(8); PG8_WAIT_L(0); PG8_BAR; PG8_MMA(0, 0, At, B0); PG8_MMA(0, 1, At, B1); PG8_BAR; PG8_SCHED;
;             PG8_LDA(At, 1, 1); PG8_STAGE(PG8_SB(1, 0), b3, voffB); PG8_STAGE(PG8_SB(1, 1), b3 + hstepB, voffB); PG8_STAGE(PG8_SA(1, 0), a3, voffA);
;             PG8_WAIT_V(8); PG8_WAIT_L(0); PG8_BAR; PG8_MMA(1, 0, At, B0); PG8_MMA(1, 1, At, B1); PG8_BAR; PG8_SCHED;
	ds_read_b128 v[132:135], v153 offset:32768
	ds_read_b128 v[136:139], v153 offset:33792
	ds_read_b128 v[140:143], v153 offset:34816
	ds_read_b128 v[144:147], v153 offset:35840
	ds_read_b128 v[148:151], v153 offset:49152
	ds_read_b128 v[178:181], v153 offset:50176
	ds_read_b128 v[182:185], v153 offset:51200
	ds_read_b128 v[212:215], v153 offset:52224
	s_mov_b32 m0, s28
	ds_read_b128 v[216:219], v205 offset:32768
	ds_read_b128 v[220:223], v205 offset:33792
	ds_read_b128 v[224:227], v205 offset:34816
	ds_read_b128 v[228:231], v205 offset:35840
	ds_read_b128 v[232:235], v205 offset:36864
	ds_read_b128 v[236:239], v205 offset:37888
	ds_read_b128 v[240:243], v205 offset:38912
	ds_read_b128 v[244:247], v205 offset:39936
	global_load_lds_dwordx4 v249, s[100:101]
	s_mov_b32 m0, s29
	s_nop 0
	global_load_lds_dwordx4 v250, s[100:101]
	s_waitcnt vmcnt(8)
	s_waitcnt lgkmcnt(0)
	s_barrier
	s_setprio 1
	v_mfma_f32_16x16x32_bf16 v[126:129], v[132:135], v[216:219], v[126:129]
	v_mfma_f32_16x16x32_bf16 v[122:125], v[140:143], v[216:219], v[122:125]
	v_mfma_f32_16x16x32_bf16 v[118:121], v[132:135], v[224:227], v[118:121]
	v_mfma_f32_16x16x32_bf16 v[114:117], v[140:143], v[224:227], v[114:117]
	v_mfma_f32_16x16x32_bf16 v[110:113], v[132:135], v[232:235], v[110:113]
	v_mfma_f32_16x16x32_bf16 v[106:109], v[140:143], v[232:235], v[106:109]
	v_mfma_f32_16x16x32_bf16 v[102:105], v[132:135], v[240:243], v[102:105]
	v_mfma_f32_16x16x32_bf16 v[98:101], v[140:143], v[240:243], v[98:101]
	v_mfma_f32_16x16x32_bf16 v[126:129], v[136:139], v[220:223], v[126:129]
	v_mfma_f32_16x16x32_bf16 v[122:125], v[144:147], v[220:223], v[122:125]
	v_mfma_f32_16x16x32_bf16 v[118:121], v[136:139], v[228:231], v[118:121]
	v_mfma_f32_16x16x32_bf16 v[114:117], v[144:147], v[228:231], v[114:117]
	v_mfma_f32_16x16x32_bf16 v[110:113], v[136:139], v[236:239], v[110:113]
	v_mfma_f32_16x16x32_bf16 v[106:109], v[144:147], v[236:239], v[106:109]
	v_mfma_f32_16x16x32_bf16 v[102:105], v[136:139], v[244:247], v[102:105]
	v_mfma_f32_16x16x32_bf16 v[98:101], v[144:147], v[244:247], v[98:101]
	s_setprio 0
	s_setprio 1
	v_mfma_f32_16x16x32_bf16 v[94:97], v[148:151], v[216:219], v[94:97]
	s_add_i32 s66, s68, s31
	v_mfma_f32_16x16x32_bf16 v[90:93], v[182:185], v[216:219], v[90:93]
	s_add_u32 s12, s12, s46
	v_mfma_f32_16x16x32_bf16 v[86:89], v[148:151], v[224:227], v[86:89]
	s_addc_u32 s13, s13, s47
	v_mfma_f32_16x16x32_bf16 v[82:85], v[182:185], v[224:227], v[82:85]
	s_mov_b32 m0, s66
	v_mfma_f32_16x16x32_bf16 v[78:81], v[148:151], v[232:235], v[78:81]
	v_mfma_f32_16x16x32_bf16 v[74:77], v[182:185], v[232:235], v[74:77]
	v_mfma_f32_16x16x32_bf16 v[70:73], v[148:151], v[240:243], v[70:73]
	v_mfma_f32_16x16x32_bf16 v[66:69], v[182:185], v[240:243], v[66:69]
	v_mfma_f32_16x16x32_bf16 v[94:97], v[178:181], v[220:223], v[94:97]
	v_mfma_f32_16x16x32_bf16 v[90:93], v[212:215], v[220:223], v[90:93]
	v_mfma_f32_16x16x32_bf16 v[86:89], v[178:181], v[228:231], v[86:89]
	v_mfma_f32_16x16x32_bf16 v[82:85], v[212:215], v[228:231], v[82:85]
	v_mfma_f32_16x16x32_bf16 v[78:81], v[178:181], v[236:239], v[78:81]
	v_mfma_f32_16x16x32_bf16 v[74:77], v[212:215], v[236:239], v[74:77]
	v_mfma_f32_16x16x32_bf16 v[70:73], v[178:181], v[244:247], v[70:73]
	v_mfma_f32_16x16x32_bf16 v[66:69], v[212:215], v[244:247], v[66:69]
	s_setprio 0
	s_barrier
	ds_read_b128 v[216:219], v205 offset:49152
	ds_read_b128 v[220:223], v205 offset:50176
	ds_read_b128 v[224:227], v205 offset:51200
	ds_read_b128 v[228:231], v205 offset:52224
	ds_read_b128 v[232:235], v205 offset:53248
	ds_read_b128 v[236:239], v205 offset:54272
	ds_read_b128 v[240:243], v205 offset:55296
	ds_read_b128 v[244:247], v205 offset:56320
	global_load_lds_dwordx4 v156, s[12:13]
	s_add_i32 m0, s66, 0x2000
	s_add_i32 s66, s69, s31
	global_load_lds_dwordx4 v158, s[12:13]
	s_add_u32 s12, s12, 0x40000
	s_addc_u32 s13, s13, 0
	s_mov_b32 m0, s66
	s_nop 0
	global_load_lds_dwordx4 v156, s[12:13]
	s_add_i32 m0, s66, 0x2000
	s_nop 0
	global_load_lds_dwordx4 v158, s[12:13]
	s_mov_b32 m0, s0
	s_nop 0
	global_load_lds_dwordx4 v251, s[100:101]
	s_mov_b32 m0, s1
	s_nop 0
	global_load_lds_dwordx4 v252, s[100:101]
	s_waitcnt vmcnt(8)
	s_waitcnt lgkmcnt(0)
	s_barrier
	s_setprio 1
	v_mfma_f32_16x16x32_bf16 v[62:65], v[132:135], v[216:219], v[62:65]
	v_mfma_f32_16x16x32_bf16 v[58:61], v[140:143], v[216:219], v[58:61]
	v_mfma_f32_16x16x32_bf16 v[54:57], v[132:135], v[224:227], v[54:57]
	v_mfma_f32_16x16x32_bf16 v[50:53], v[140:143], v[224:227], v[50:53]
	v_mfma_f32_16x16x32_bf16 v[46:49], v[132:135], v[232:235], v[46:49]
	v_mfma_f32_16x16x32_bf16 v[42:45], v[140:143], v[232:235], v[42:45]
	v_mfma_f32_16x16x32_bf16 v[38:41], v[132:135], v[240:243], v[38:41]
	v_mfma_f32_16x16x32_bf16 v[34:37], v[140:143], v[240:243], v[34:37]
	v_mfma_f32_16x16x32_bf16 v[62:65], v[136:139], v[220:223], v[62:65]
	v_mfma_f32_16x16x32_bf16 v[58:61], v[144:147], v[220:223], v[58:61]
	v_mfma_f32_16x16x32_bf16 v[54:57], v[136:139], v[228:231], v[54:57]
	v_mfma_f32_16x16x32_bf16 v[50:53], v[144:147], v[228:231], v[50:53]
	v_mfma_f32_16x16x32_bf16 v[46:49], v[136:139], v[236:239], v[46:49]
	v_mfma_f32_16x16x32_bf16 v[42:45], v[144:147], v[236:239], v[42:45]
	v_mfma_f32_16x16x32_bf16 v[38:41], v[136:139], v[244:247], v[38:41]
	v_mfma_f32_16x16x32_bf16 v[34:37], v[144:147], v[244:247], v[34:37]
	s_setprio 0
	s_setprio 1
	v_mfma_f32_16x16x32_bf16 v[30:33], v[148:151], v[216:219], v[30:33]
	s_add_i32 s65, s65, 2
	v_mfma_f32_16x16x32_bf16 v[26:29], v[182:185], v[216:219], v[26:29]
	s_add_u32 s63, s63, 0x100
	v_mfma_f32_16x16x32_bf16 v[22:25], v[148:151], v[224:227], v[22:25]
	s_addc_u32 s64, s64, 0
	v_mfma_f32_16x16x32_bf16 v[18:21], v[182:185], v[224:227], v[18:21]
	s_add_u32 s10, s10, 0x10000
	v_mfma_f32_16x16x32_bf16 v[14:17], v[148:151], v[232:235], v[14:17]
	s_addc_u32 s11, s11, 0
	v_mfma_f32_16x16x32_bf16 v[10:13], v[182:185], v[232:235], v[10:13]
	s_mov_b64 s[12:13], 0x10000
	v_mfma_f32_16x16x32_bf16 v[6:9], v[148:151], v[240:243], v[6:9]
	s_cmp_gt_u32 s65, 13
	v_mfma_f32_16x16x32_bf16 v[2:5], v[182:185], v[240:243], v[2:5]
	v_mfma_f32_16x16x32_bf16 v[30:33], v[178:181], v[220:223], v[30:33]
	v_mfma_f32_16x16x32_bf16 v[26:29], v[212:215], v[220:223], v[26:29]
	v_mfma_f32_16x16x32_bf16 v[22:25], v[178:181], v[228:231], v[22:25]
	v_mfma_f32_16x16x32_bf16 v[18:21], v[212:215], v[228:231], v[18:21]
	v_mfma_f32_16x16x32_bf16 v[14:17], v[178:181], v[236:239], v[14:17]
	v_mfma_f32_16x16x32_bf16 v[10:13], v[212:215], v[236:239], v[10:13]
	v_mfma_f32_16x16x32_bf16 v[6:9], v[178:181], v[244:247], v[6:9]
	v_mfma_f32_16x16x32_bf16 v[2:5], v[212:215], v[244:247], v[2:5]
	s_setprio 0
	s_barrier
	s_cbranch_scc0 .LBB0_818
	s_and_b64 vcc, exec, s[52:53]
	s_cbranch_vccz .LBB0_821
	s_barrier

; #define PG8_STAGE(bufoff, gbase, voff) do { _Pragma("unroll") for (int _i = 0; _i < 2; ++_i) \
;         __builtin_amdgcn_global_load_lds((const unsigned*)((const char*)(gbase) + (voff)[_i]), (PG8_LAS unsigned*)(lds + (bufoff) + ldsw + _i * 8192), 16, 0, 0); } while (0)
; #define PG8_LDA(dst, b, h) do { _Pragma("unroll") for (int m = 0; m < 4; ++m) _Pragma("unroll") for (int k = 0; k < 2; ++k) dst[m][k] = *(const PG8_LAS bf16x8*)(lds + PG8_SA(b, h) + aoff + m * 2048 + k * 1024); } while (0)
; #define PG8_LDB(dst, b, h) do { _Pragma("unroll") for (int n = 0; n < 2; ++n) _Pragma("unroll") for (int k = 0; k < 2; ++k) dst[n][k] = *(const PG8_LAS bf16x8*)(lds + PG8_SB(b, h) + boff + n * 2048 + k * 1024); } while (0)
; #define PG8_MMA(ai, bj, At, Bt) do { __builtin_amdgcn_s_setprio(1); _Pragma("unroll") for (int m = 0; m < 4; ++m) _Pragma("unroll") for (int n = 0; n < 2; ++n) _Pragma("unroll") for (int k = 0; k < 2; ++k) \
;         acc[ai][bj][m][n] = __builtin_amdgcn_mfma_f32_16x16x32_bf16(Bt[n][k], At[m][k], acc[ai][bj][m][n], 0, 0, 0); __builtin_amdgcn_s_setprio(0); } while (0)
; #define PG8_WAIT_V(n) asm volatile("s_waitcnt vmcnt(" #n ")" ::: "memory")
; template <class Epi, bool ALIGN_EPI, bool ABLK = false>
; __device__ __forceinline__ void gemm_phase(PG8_LAS unsigned char* lds, const Gemm g, const StaticOrder& S, const Epi& E) {
;     ...
;         const bool has_next = S.next(ui + 1, nxt);
;         const char* nA = has_next ? PG8_ABASE(nxt) : cA; const char* nB = has_next ? PG8_BBASE(nxt) : cB;
;         for (int t = 0; t < nt; t += 2) {
;             const bool last = (t == nt - 2);
;             const char* a1 = cA + (size_t)(t + 1) * kstepA;
;             const char* a2 = last ? nA : cA + (size_t)(t + 2) * kstepA; const char* b2 = last ? nB : cB + (size_t)(t + 2) * kstepB;
;             const char* a3 = a2 + kstepA; const char* b3 = b2 + kstepB;
;             PG8_LDB(B0, 0, 0); PG8_LDB(B1, 0, 1); PG8_SCHED; PG8_LDA(At, 0, 0); PG8_STAGE(PG8_SA(1, 1), a1 + hstepA, voffA);
;             PG8_WAIT_V(8); PG8_WAIT_L(0); PG8_BAR; PG8_MMA(0, 0, At, B0); PG8_MMA(0, 1, At, B1); PG8_BAR; PG8_SCHED;
;             PG8_LDA(At, 0, 1); PG8_STAGE(PG8_SB(0, 0), b2, voffB); PG8_STAGE(PG8_SB(0, 1), b2 + hstepB, voffB); PG8_STAGE(PG8_SA(0, 0), a2, voffA);
;             PG8_WAIT_V(8); PG8_WAIT_L(0); PG8_BAR; PG8_MMA(1, 0, At, B0); PG8_MMA(1, 1, At, B1); PG8_BAR; PG8_SCHED;
.LBB0_2495:
	ds_read_b128 v[132:135], v251
	ds_read_b128 v[178:181], v251 offset:1024
	ds_read_b128 v[182:185], v251 offset:2048
	ds_read_b128 v[186:189], v251 offset:3072
	ds_read_b128 v[190:193], v251 offset:16384
	ds_read_b128 v[194:197], v251 offset:17408
	ds_read_b128 v[198:201], v251 offset:18432
	ds_read_b128 v[202:205], v251 offset:19456
	s_add_u32 s60, s24, s58
	s_addc_u32 s61, s25, s59
	s_sub_u32 s98, s60, 0x10000
	s_subb_u32 s99, s61, 0
	s_add_i32 m0, s66, 0xc000
	ds_read_b128 v[206:209], v176
	ds_read_b128 v[210:213], v176 offset:1024
	ds_read_b128 v[214:217], v176 offset:2048
	ds_read_b128 v[218:221], v176 offset:3072
	ds_read_b128 v[222:225], v176 offset:4096
	ds_read_b128 v[226:229], v176 offset:5120
	ds_read_b128 v[230:233], v176 offset:6144
	ds_read_b128 v[234:237], v176 offset:7168
	global_load_lds_dwordx4 v249, s[98:99]
	s_add_i32 m0, s66, 0xe000
	s_nop 0
	global_load_lds_dwordx4 v250, s[98:99]
	s_waitcnt vmcnt(8)
	s_waitcnt lgkmcnt(0)
	s_barrier
	s_setprio 1
	v_mfma_f32_16x16x32_bf16 v[126:129], v[132:135], v[206:209], v[126:129]
	v_mfma_f32_16x16x32_bf16 v[122:125], v[182:185], v[206:209], v[122:125]
	v_mfma_f32_16x16x32_bf16 v[118:121], v[132:135], v[214:217], v[118:121]
	v_mfma_f32_16x16x32_bf16 v[114:117], v[182:185], v[214:217], v[114:117]
	v_mfma_f32_16x16x32_bf16 v[110:113], v[132:135], v[222:225], v[110:113]
	v_mfma_f32_16x16x32_bf16 v[106:109], v[182:185], v[222:225], v[106:109]
	v_mfma_f32_16x16x32_bf16 v[102:105], v[132:135], v[230:233], v[102:105]
	v_mfma_f32_16x16x32_bf16 v[98:101], v[182:185], v[230:233], v[98:101]
	v_mfma_f32_16x16x32_bf16 v[126:129], v[178:181], v[210:213], v[126:129]
	v_mfma_f32_16x16x32_bf16 v[122:125], v[186:189], v[210:213], v[122:125]
	v_mfma_f32_16x16x32_bf16 v[118:121], v[178:181], v[218:221], v[118:121]
	v_mfma_f32_16x16x32_bf16 v[114:117], v[186:189], v[218:221], v[114:117]
	v_mfma_f32_16x16x32_bf16 v[110:113], v[178:181], v[226:229], v[110:113]
	v_mfma_f32_16x16x32_bf16 v[106:109], v[186:189], v[226:229], v[106:109]
	v_mfma_f32_16x16x32_bf16 v[102:105], v[178:181], v[234:237], v[102:105]
	v_mfma_f32_16x16x32_bf16 v[98:101], v[186:189], v[234:237], v[98:101]
	s_setprio 0
	s_setprio 1
	v_mfma_f32_16x16x32_bf16 v[94:97], v[190:193], v[206:209], v[94:97]
	s_add_i32 s86, s75, s9
	v_mfma_f32_16x16x32_bf16 v[90:93], v[198:201], v[206:209], v[90:93]
	s_mov_b32 m0, s86
	v_mfma_f32_16x16x32_bf16 v[86:89], v[190:193], v[214:217], v[86:89]
	s_cmp_eq_u32 s83, 12
	s_cselect_b32 s101, s53, s61
	v_mfma_f32_16x16x32_bf16 v[82:85], v[198:201], v[214:217], v[82:85]
	s_cselect_b32 s100, s79, s60
	s_cselect_b32 s61, s51, s82
	v_mfma_f32_16x16x32_bf16 v[78:81], v[190:193], v[222:225], v[78:81]
	s_cselect_b32 s60, s80, s81
	v_mfma_f32_16x16x32_bf16 v[74:77], v[198:201], v[222:225], v[74:77]
	v_mfma_f32_16x16x32_bf16 v[70:73], v[190:193], v[230:233], v[70:73]
	v_mfma_f32_16x16x32_bf16 v[66:69], v[198:201], v[230:233], v[66:69]
	v_mfma_f32_16x16x32_bf16 v[94:97], v[194:197], v[210:213], v[94:97]
	v_mfma_f32_16x16x32_bf16 v[90:93], v[202:205], v[210:213], v[90:93]
	v_mfma_f32_16x16x32_bf16 v[86:89], v[194:197], v[218:221], v[86:89]
	v_mfma_f32_16x16x32_bf16 v[82:85], v[202:205], v[218:221], v[82:85]
	v_mfma_f32_16x16x32_bf16 v[78:81], v[194:197], v[226:229], v[78:81]
	v_mfma_f32_16x16x32_bf16 v[74:77], v[202:205], v[226:229], v[74:77]
	v_mfma_f32_16x16x32_bf16 v[70:73], v[194:197], v[234:237], v[70:73]
	v_mfma_f32_16x16x32_bf16 v[66:69], v[202:205], v[234:237], v[66:69]
	s_setprio 0
	s_barrier
	ds_read_b128 v[206:209], v176 offset:16384
	ds_read_b128 v[210:213], v176 offset:17408
	ds_read_b128 v[214:217], v176 offset:18432
	ds_read_b128 v[218:221], v176 offset:19456
	ds_read_b128 v[222:225], v176 offset:20480
	ds_read_b128 v[226:229], v176 offset:21504
	ds_read_b128 v[230:233], v176 offset:22528
	ds_read_b128 v[234:237], v176 offset:23552
	global_load_lds_dwordx4 v140, s[60:61]
	s_add_i32 m0, s86, 0x2000
	s_add_u32 s86, s60, 0x40000
	s_addc_u32 s87, s61, 0
	s_add_i32 s88, s76, s9
	global_load_lds_dwordx4 v142, s[60:61]
	s_mov_b32 m0, s88
	s_nop 0
	global_load_lds_dwordx4 v140, s[86:87]
	s_add_i32 m0, s88, 0x2000
	s_nop 0
	global_load_lds_dwordx4 v142, s[86:87]
	s_mov_b32 m0, s66
	s_nop 0
	global_load_lds_dwordx4 v138, s[100:101]
	s_mov_b32 m0, s67
	s_nop 0
	global_load_lds_dwordx4 v244, s[100:101]
	s_waitcnt vmcnt(8)
	s_waitcnt lgkmcnt(0)
	s_barrier
	s_setprio 1
	v_mfma_f32_16x16x32_bf16 v[62:65], v[132:135], v[206:209], v[62:65]
	v_mfma_f32_16x16x32_bf16 v[58:61], v[182:185], v[206:209], v[58:61]
	v_mfma_f32_16x16x32_bf16 v[54:57], v[132:135], v[214:217], v[54:57]
	v_mfma_f32_16x16x32_bf16 v[50:53], v[182:185], v[214:217], v[50:53]
	v_mfma_f32_16x16x32_bf16 v[46:49], v[132:135], v[222:225], v[46:49]
	v_mfma_f32_16x16x32_bf16 v[42:45], v[182:185], v[222:225], v[42:45]
	v_mfma_f32_16x16x32_bf16 v[38:41], v[132:135], v[230:233], v[38:41]
	v_mfma_f32_16x16x32_bf16 v[34:37], v[182:185], v[230:233], v[34:37]
	v_mfma_f32_16x16x32_bf16 v[62:65], v[178:181], v[210:213], v[62:65]
	v_mfma_f32_16x16x32_bf16 v[58:61], v[186:189], v[210:213], v[58:61]
	v_mfma_f32_16x16x32_bf16 v[54:57], v[178:181], v[218:221], v[54:57]
	v_mfma_f32_16x16x32_bf16 v[50:53], v[186:189], v[218:221], v[50:53]
	v_mfma_f32_16x16x32_bf16 v[46:49], v[178:181], v[226:229], v[46:49]
	v_mfma_f32_16x16x32_bf16 v[42:45], v[186:189], v[226:229], v[42:45]
	v_mfma_f32_16x16x32_bf16 v[38:41], v[178:181], v[234:237], v[38:41]
	v_mfma_f32_16x16x32_bf16 v[34:37], v[186:189], v[234:237], v[34:37]
	s_setprio 0
	s_setprio 1
	v_mfma_f32_16x16x32_bf16 v[30:33], v[190:193], v[206:209], v[30:33]
	s_add_i32 s84, 0, 0x18000
	v_mfma_f32_16x16x32_bf16 v[26:29], v[198:201], v[206:209], v[26:29]
	s_add_i32 s85, 0, 0x1c000
	v_mfma_f32_16x16x32_bf16 v[22:25], v[190:193], v[214:217], v[22:25]
	v_mfma_f32_16x16x32_bf16 v[18:21], v[198:201], v[214:217], v[18:21]
	v_mfma_f32_16x16x32_bf16 v[14:17], v[190:193], v[222:225], v[14:17]
	v_mfma_f32_16x16x32_bf16 v[10:13], v[198:201], v[222:225], v[10:13]
	v_mfma_f32_16x16x32_bf16 v[6:9], v[190:193], v[230:233], v[6:9]
	v_mfma_f32_16x16x32_bf16 v[2:5], v[198:201], v[230:233], v[2:5]
	v_mfma_f32_16x16x32_bf16 v[30:33], v[194:197], v[210:213], v[30:33]
	v_mfma_f32_16x16x32_bf16 v[26:29], v[202:205], v[210:213], v[26:29]
	v_mfma_f32_16x16x32_bf16 v[22:25], v[194:197], v[218:221], v[22:25]
	v_mfma_f32_16x16x32_bf16 v[18:21], v[202:205], v[218:221], v[18:21]
	v_mfma_f32_16x16x32_bf16 v[14:17], v[194:197], v[226:229], v[14:17]
	v_mfma_f32_16x16x32_bf16 v[10:13], v[202:205], v[226:229], v[10:13]
	v_mfma_f32_16x16x32_bf16 v[6:9], v[194:197], v[234:237], v[6:9]
	v_mfma_f32_16x16x32_bf16 v[2:5], v[202:205], v[234:237], v[2:5]
	s_setprio 0
	s_barrier
; #define PG8_STAGE(bufoff, gbase, voff) do { _Pragma("unroll") for (int _i = 0; _i < 2; ++_i) \
;         __builtin_amdgcn_global_load_lds((const unsigned*)((const char*)(gbase) + (voff)[_i]), (PG8_LAS unsigned*)(lds + (bufoff) + ldsw + _i * 8192), 16, 0, 0); } while (0)
; #define PG8_LDA(dst, b, h) do { _Pragma("unroll") for (int m = 0; m < 4; ++m) _Pragma("unroll") for (int k = 0; k < 2; ++k) dst[m][k] = *(const PG8_LAS bf16x8*)(lds + PG8_SA(b, h) + aoff + m * 2048 + k * 1024); } while (0)
; #define PG8_LDB(dst, b, h) do { _Pragma("unroll") for (int n = 0; n < 2; ++n) _Pragma("unroll") for (int k = 0; k < 2; ++k) dst[n][k] = *(const PG8_LAS bf16x8*)(lds + PG8_SB(b, h) + boff + n * 2048 + k * 1024); } while (0)
; #define PG8_MMA(ai, bj, At, Bt) do { __builtin_amdgcn_s_setprio(1); _Pragma("unroll") for (int m = 0; m < 4; ++m) _Pragma("unroll") for (int n = 0; n < 2; ++n) _Pragma("unroll") for (int k = 0; k < 2; ++k) \
;         acc[ai][bj][m][n] = __builtin_amdgcn_mfma_f32_16x16x32_bf16(Bt[n][k], At[m][k], acc[ai][bj][m][n], 0, 0, 0); __builtin_amdgcn_s_setprio(0); } while (0)
; #define PG8_WAIT_V(n) asm volatile("s_waitcnt vmcnt(" #n ")" ::: "memory")
; #define PG8_WAIT_L(n) asm volatile("s_waitcnt lgkmcnt(" #n ")" ::: "memory")
; #define PG8_BAR __builtin_amdgcn_s_barrier()
; #define PG8_SCHED __builtin_amdgcn_sched_barrier(0)
; template <class Epi, bool ALIGN_EPI, bool ABLK = false>
; __device__ __forceinline__ void gemm_phase(PG8_LAS unsigned char* lds, const Gemm g, const StaticOrder& S, const Epi& E) {
;     ...
;             PG8_LDB(B0, 1, 0); PG8_LDB(B1, 1, 1); PG8_SCHED; PG8_LDA(At, 1, 0); PG8_STAGE(PG8_SA(0, 1), a2 + hstepA, voffA);
;             PG8_WAIT_V(8); PG8_WAIT_L(0); PG8_BAR; PG8_MMA(0, 0, At, B0); PG8_MMA(0, 1, At, B1); PG8_BAR; PG8_SCHED;
;             PG8_LDA(At, 1, 1); PG8_STAGE(PG8_SB(1, 0), b3, voffB); PG8_STAGE(PG8_SB(1, 1), b3 + hstepB, voffB); PG8_STAGE(PG8_SA(1, 0), a3, voffA);
;             PG8_WAIT_V(8); PG8_WAIT_L(0); PG8_BAR; PG8_MMA(1, 0, At, B0); PG8_MMA(1, 1, At, B1); PG8_BAR; PG8_SCHED;
	ds_read_b128 v[132:135], v251 offset:32768
	ds_read_b128 v[178:181], v251 offset:33792
	ds_read_b128 v[182:185], v251 offset:34816
	ds_read_b128 v[186:189], v251 offset:35840
	ds_read_b128 v[190:193], v251 offset:49152
	ds_read_b128 v[194:197], v251 offset:50176
	ds_read_b128 v[198:201], v251 offset:51200
	ds_read_b128 v[202:205], v251 offset:52224
	s_mov_b32 m0, s68
	ds_read_b128 v[206:209], v176 offset:32768
	ds_read_b128 v[210:213], v176 offset:33792
	ds_read_b128 v[214:217], v176 offset:34816
	ds_read_b128 v[218:221], v176 offset:35840
	ds_read_b128 v[222:225], v176 offset:36864
	ds_read_b128 v[226:229], v176 offset:37888
	ds_read_b128 v[230:233], v176 offset:38912
	ds_read_b128 v[234:237], v176 offset:39936
	global_load_lds_dwordx4 v245, s[100:101]
	s_mov_b32 m0, s69
	s_nop 0
	global_load_lds_dwordx4 v246, s[100:101]
	s_waitcnt vmcnt(8)
	s_waitcnt lgkmcnt(0)
	s_barrier
	s_setprio 1
	v_mfma_f32_16x16x32_bf16 v[126:129], v[132:135], v[206:209], v[126:129]
	v_mfma_f32_16x16x32_bf16 v[122:125], v[182:185], v[206:209], v[122:125]
	v_mfma_f32_16x16x32_bf16 v[118:121], v[132:135], v[214:217], v[118:121]
	v_mfma_f32_16x16x32_bf16 v[114:117], v[182:185], v[214:217], v[114:117]
	v_mfma_f32_16x16x32_bf16 v[110:113], v[132:135], v[222:225], v[110:113]
	v_mfma_f32_16x16x32_bf16 v[106:109], v[182:185], v[222:225], v[106:109]
	v_mfma_f32_16x16x32_bf16 v[102:105], v[132:135], v[230:233], v[102:105]
	v_mfma_f32_16x16x32_bf16 v[98:101], v[182:185], v[230:233], v[98:101]
	v_mfma_f32_16x16x32_bf16 v[126:129], v[178:181], v[210:213], v[126:129]
	v_mfma_f32_16x16x32_bf16 v[122:125], v[186:189], v[210:213], v[122:125]
	v_mfma_f32_16x16x32_bf16 v[118:121], v[178:181], v[218:221], v[118:121]
	v_mfma_f32_16x16x32_bf16 v[114:117], v[186:189], v[218:221], v[114:117]
	v_mfma_f32_16x16x32_bf16 v[110:113], v[178:181], v[226:229], v[110:113]
	v_mfma_f32_16x16x32_bf16 v[106:109], v[186:189], v[226:229], v[106:109]
	v_mfma_f32_16x16x32_bf16 v[102:105], v[178:181], v[234:237], v[102:105]
	v_mfma_f32_16x16x32_bf16 v[98:101], v[186:189], v[234:237], v[98:101]
	s_setprio 0
	s_setprio 1
	v_mfma_f32_16x16x32_bf16 v[94:97], v[190:193], v[206:209], v[94:97]
	s_add_i32 s84, s84, s9
	v_mfma_f32_16x16x32_bf16 v[90:93], v[198:201], v[206:209], v[90:93]
	s_add_u32 s60, s60, s28
	v_mfma_f32_16x16x32_bf16 v[86:89], v[190:193], v[214:217], v[86:89]
	s_addc_u32 s61, s61, s29
	v_mfma_f32_16x16x32_bf16 v[82:85], v[198:201], v[214:217], v[82:85]
	s_mov_b32 m0, s84
	v_mfma_f32_16x16x32_bf16 v[78:81], v[190:193], v[222:225], v[78:81]
	v_mfma_f32_16x16x32_bf16 v[74:77], v[198:201], v[222:225], v[74:77]
	v_mfma_f32_16x16x32_bf16 v[70:73], v[190:193], v[230:233], v[70:73]
	v_mfma_f32_16x16x32_bf16 v[66:69], v[198:201], v[230:233], v[66:69]
	v_mfma_f32_16x16x32_bf16 v[94:97], v[194:197], v[210:213], v[94:97]
	v_mfma_f32_16x16x32_bf16 v[90:93], v[202:205], v[210:213], v[90:93]
	v_mfma_f32_16x16x32_bf16 v[86:89], v[194:197], v[218:221], v[86:89]
	v_mfma_f32_16x16x32_bf16 v[82:85], v[202:205], v[218:221], v[82:85]
	v_mfma_f32_16x16x32_bf16 v[78:81], v[194:197], v[226:229], v[78:81]
	v_mfma_f32_16x16x32_bf16 v[74:77], v[202:205], v[226:229], v[74:77]
	v_mfma_f32_16x16x32_bf16 v[70:73], v[194:197], v[234:237], v[70:73]
	v_mfma_f32_16x16x32_bf16 v[66:69], v[202:205], v[234:237], v[66:69]
	s_setprio 0
	s_barrier
	ds_read_b128 v[206:209], v176 offset:49152
	ds_read_b128 v[210:213], v176 offset:50176
	ds_read_b128 v[214:217], v176 offset:51200
	ds_read_b128 v[218:221], v176 offset:52224
	ds_read_b128 v[222:225], v176 offset:53248
	ds_read_b128 v[226:229], v176 offset:54272
	ds_read_b128 v[230:233], v176 offset:55296
	ds_read_b128 v[234:237], v176 offset:56320
	global_load_lds_dwordx4 v140, s[60:61]
	s_add_i32 m0, s84, 0x2000
	s_add_i32 s84, s85, s9
	global_load_lds_dwordx4 v142, s[60:61]
	s_add_u32 s60, s60, 0x40000
	s_addc_u32 s61, s61, 0
	s_mov_b32 m0, s84
	s_nop 0
	global_load_lds_dwordx4 v140, s[60:61]
	s_add_i32 m0, s84, 0x2000
	s_nop 0
	global_load_lds_dwordx4 v142, s[60:61]
	s_mov_b32 m0, s70
	s_nop 0
	global_load_lds_dwordx4 v247, s[100:101]
	s_mov_b32 m0, s72
	s_nop 0
	global_load_lds_dwordx4 v248, s[100:101]
	s_waitcnt vmcnt(8)
	s_waitcnt lgkmcnt(0)
	s_barrier
	s_setprio 1
	v_mfma_f32_16x16x32_bf16 v[62:65], v[132:135], v[206:209], v[62:65]
	v_mfma_f32_16x16x32_bf16 v[58:61], v[182:185], v[206:209], v[58:61]
	v_mfma_f32_16x16x32_bf16 v[54:57], v[132:135], v[214:217], v[54:57]
	v_mfma_f32_16x16x32_bf16 v[50:53], v[182:185], v[214:217], v[50:53]
	v_mfma_f32_16x16x32_bf16 v[46:49], v[132:135], v[222:225], v[46:49]
	v_mfma_f32_16x16x32_bf16 v[42:45], v[182:185], v[222:225], v[42:45]
	v_mfma_f32_16x16x32_bf16 v[38:41], v[132:135], v[230:233], v[38:41]
	v_mfma_f32_16x16x32_bf16 v[34:37], v[182:185], v[230:233], v[34:37]
	v_mfma_f32_16x16x32_bf16 v[62:65], v[178:181], v[210:213], v[62:65]
	v_mfma_f32_16x16x32_bf16 v[58:61], v[186:189], v[210:213], v[58:61]
	v_mfma_f32_16x16x32_bf16 v[54:57], v[178:181], v[218:221], v[54:57]
	v_mfma_f32_16x16x32_bf16 v[50:53], v[186:189], v[218:221], v[50:53]
	v_mfma_f32_16x16x32_bf16 v[46:49], v[178:181], v[226:229], v[46:49]
	v_mfma_f32_16x16x32_bf16 v[42:45], v[186:189], v[226:229], v[42:45]
	v_mfma_f32_16x16x32_bf16 v[38:41], v[178:181], v[234:237], v[38:41]
	v_mfma_f32_16x16x32_bf16 v[34:37], v[186:189], v[234:237], v[34:37]
	s_setprio 0
	s_setprio 1
	v_mfma_f32_16x16x32_bf16 v[30:33], v[190:193], v[206:209], v[30:33]
	s_add_i32 s83, s83, 2
	v_mfma_f32_16x16x32_bf16 v[26:29], v[198:201], v[206:209], v[26:29]
	s_add_u32 s81, s81, 0x100
	v_mfma_f32_16x16x32_bf16 v[22:25], v[190:193], v[214:217], v[22:25]
	s_addc_u32 s82, s82, 0
	v_mfma_f32_16x16x32_bf16 v[18:21], v[198:201], v[214:217], v[18:21]
	s_add_u32 s58, s58, 0x10000
	v_mfma_f32_16x16x32_bf16 v[14:17], v[190:193], v[222:225], v[14:17]
	s_addc_u32 s59, s59, 0
	v_mfma_f32_16x16x32_bf16 v[10:13], v[198:201], v[222:225], v[10:13]
	s_cmp_gt_u32 s83, 13
	v_mfma_f32_16x16x32_bf16 v[6:9], v[190:193], v[230:233], v[6:9]
	v_mfma_f32_16x16x32_bf16 v[2:5], v[198:201], v[230:233], v[2:5]
	v_mfma_f32_16x16x32_bf16 v[30:33], v[194:197], v[210:213], v[30:33]
	v_mfma_f32_16x16x32_bf16 v[26:29], v[202:205], v[210:213], v[26:29]
	v_mfma_f32_16x16x32_bf16 v[22:25], v[194:197], v[218:221], v[22:25]
	v_mfma_f32_16x16x32_bf16 v[18:21], v[202:205], v[218:221], v[18:21]
	v_mfma_f32_16x16x32_bf16 v[14:17], v[194:197], v[226:229], v[14:17]
	v_mfma_f32_16x16x32_bf16 v[10:13], v[202:205], v[226:229], v[10:13]
	v_mfma_f32_16x16x32_bf16 v[6:9], v[194:197], v[234:237], v[6:9]
	v_mfma_f32_16x16x32_bf16 v[2:5], v[202:205], v[234:237], v[2:5]
	s_setprio 0
	s_barrier
	s_cbranch_scc0 .LBB0_2495
	s_and_b64 vcc, exec, s[36:37]
	s_cbranch_vccz .LBB0_2498
	s_barrier
